# column-sliced PEER gather, removed racy stand-in loads in the sub-phase prologue
# speedup vs baseline: 1.7276x; 1.0015x over previous
.Lgy_A_1:
	v_lshrrev_b32_e32 v142, 6, v162
	v_readlane_b32 s2, v242, 0
	v_readlane_b32 s59, v241, 24
	v_readfirstlane_b32 s29, v142
	s_and_b32 s28, s2, 7
	s_lshr_b32 s2, s2, 3
	s_lshl_b32 s2, s2, 2
	s_add_u32 s54, s2, s29
	s_lshr_b32 s59, s59, 3
	s_load_dwordx2 s[88:89], s[0:1], 0x1a8
	s_load_dwordx2 s[92:93], s[0:1], 0x130
	v_readlane_b32 s40, v240, 8
	v_readlane_b32 s41, v240, 9
	v_and_b32_e32 v142, 7, v168
	v_lshlrev_b32_e32 v160, 2, v168
	s_lshl_b32 s32, s28, 7
	v_lshl_add_u32 v138, v142, 4, s32
	v_and_b32_e32 v143, 0xf8, v168
	v_add_u32_e32 v130, 0, v143
	v_add_u32_e32 v131, 1, v143
	v_add_u32_e32 v132, 2, v143
	v_add_u32_e32 v133, 3, v143
	v_add_u32_e32 v134, 4, v143
	v_add_u32_e32 v135, 5, v143
	v_add_u32_e32 v136, 6, v143
	v_add_u32_e32 v137, 7, v143
	v_lshlrev_b32_e32 v130, 2, v130
	v_lshlrev_b32_e32 v131, 2, v131
	v_lshlrev_b32_e32 v132, 2, v132
	v_lshlrev_b32_e32 v133, 2, v133
	v_lshlrev_b32_e32 v134, 2, v134
	v_lshlrev_b32_e32 v135, 2, v135
	v_lshlrev_b32_e32 v136, 2, v136
	v_lshlrev_b32_e32 v137, 2, v137
	s_lshl_b32 s32, s28, 8
	v_lshl_add_u32 v161, v142, 5, s32
	s_mov_b32 s4, 0x01010101
	s_mov_b32 s5, 0x01010101
	s_mov_b32 s6, 0x02020202
	s_mov_b32 s7, 0x02020202
	s_mov_b32 s8, 0x04040404
	s_mov_b32 s9, 0x04040404
	s_mov_b32 s10, 0x08080808
	s_mov_b32 s11, 0x08080808
	s_mov_b32 s12, 0x10101010
	s_mov_b32 s13, 0x10101010
	s_mov_b32 s14, 0x20202020
	s_mov_b32 s15, 0x20202020
	s_mov_b32 s16, 0x40404040
	s_mov_b32 s17, 0x40404040
	s_mov_b32 s18, 0x80808080
	s_mov_b32 s19, 0x80808080
	s_waitcnt lgkmcnt(0)
	s_mul_i32 s32, s28, 0x840000
	s_add_u32 s92, s92, s32
	s_addc_u32 s93, s93, 0
	s_nop 4
	s_cmp_lt_u32 s54, 0x4200
	s_cbranch_scc0 .Lgy_Adone_6
	s_min_u32 s98, s54, 0x41ff
	s_lshl_b32 s98, s98, 9
	s_add_u32 s52, s88, s98
	s_addc_u32 s53, s89, 0
	global_load_dword v144, v160, s[52:53]
	global_load_dword v145, v160, s[52:53] offset:256
	s_add_u32 s99, s54, s59
	s_min_u32 s98, s99, 0x41ff
	s_lshl_b32 s98, s98, 9
	s_add_u32 s52, s88, s98
	s_addc_u32 s53, s89, 0
	global_load_dword v150, v160, s[52:53]
	global_load_dword v151, v160, s[52:53] offset:256
	s_min_u32 s98, s54, 0x41ff
	s_lshl_b32 s98, s98, 11
	s_add_u32 s52, s74, s98
	s_addc_u32 s53, s75, 0
	global_load_dwordx4 v[152:155], v161, s[52:53]
	global_load_dwordx4 v[156:159], v161, s[52:53] offset:16
	s_waitcnt vmcnt(0)
	ds_bpermute_b32 v16, v130, v144
	ds_bpermute_b32 v17, v131, v144
	ds_bpermute_b32 v18, v132, v144
	ds_bpermute_b32 v19, v133, v144
	ds_bpermute_b32 v20, v134, v144
	ds_bpermute_b32 v21, v135, v144
	ds_bpermute_b32 v22, v136, v144
	ds_bpermute_b32 v23, v137, v144
	ds_bpermute_b32 v24, v130, v145
	ds_bpermute_b32 v25, v131, v145
	ds_bpermute_b32 v26, v132, v145
	ds_bpermute_b32 v27, v133, v145
	ds_bpermute_b32 v28, v134, v145
	ds_bpermute_b32 v29, v135, v145
	ds_bpermute_b32 v30, v136, v145
	ds_bpermute_b32 v31, v137, v145
	s_waitcnt lgkmcnt(0)
	v_lshl_add_u32 v16, v16, 10, v138
	v_lshl_add_u32 v17, v17, 10, v138
	v_lshl_add_u32 v18, v18, 10, v138
	v_lshl_add_u32 v19, v19, 10, v138
	v_lshl_add_u32 v20, v20, 10, v138
	v_lshl_add_u32 v21, v21, 10, v138
	v_lshl_add_u32 v22, v22, 10, v138
	v_lshl_add_u32 v23, v23, 10, v138
	v_lshl_add_u32 v24, v24, 10, v138
	v_lshl_add_u32 v25, v25, 10, v138
	v_lshl_add_u32 v26, v26, 10, v138
	v_lshl_add_u32 v27, v27, 10, v138
	v_lshl_add_u32 v28, v28, 10, v138
	v_lshl_add_u32 v29, v29, 10, v138
	v_lshl_add_u32 v30, v30, 10, v138
	v_lshl_add_u32 v31, v31, 10, v138
	global_load_dwordx4 v[48:51], v16, s[40:41]
	global_load_dwordx4 v[52:55], v17, s[40:41]
	global_load_dwordx4 v[56:59], v18, s[40:41]
	global_load_dwordx4 v[60:63], v19, s[40:41]
	global_load_dwordx4 v[64:67], v20, s[40:41]
	global_load_dwordx4 v[68:71], v21, s[40:41]
	global_load_dwordx4 v[72:75], v22, s[40:41]
	global_load_dwordx4 v[76:79], v23, s[40:41]
	global_load_dwordx4 v[80:83], v24, s[40:41]
	global_load_dwordx4 v[84:87], v25, s[40:41]
	global_load_dwordx4 v[88:91], v26, s[40:41]
	global_load_dwordx4 v[92:95], v27, s[40:41]
	global_load_dwordx4 v[96:99], v28, s[40:41]
	global_load_dwordx4 v[100:103], v29, s[40:41]
	global_load_dwordx4 v[104:107], v30, s[40:41]
	global_load_dwordx4 v[108:111], v31, s[40:41]
	ds_bpermute_b32 v16, v130, v150
	ds_bpermute_b32 v17, v131, v150
	ds_bpermute_b32 v18, v132, v150
	ds_bpermute_b32 v19, v133, v150
	ds_bpermute_b32 v20, v134, v150
	ds_bpermute_b32 v21, v135, v150
	ds_bpermute_b32 v22, v136, v150
	ds_bpermute_b32 v23, v137, v150
	ds_bpermute_b32 v24, v130, v151
	ds_bpermute_b32 v25, v131, v151
	ds_bpermute_b32 v26, v132, v151
	ds_bpermute_b32 v27, v133, v151
	ds_bpermute_b32 v28, v134, v151
	ds_bpermute_b32 v29, v135, v151
	ds_bpermute_b32 v30, v136, v151
	ds_bpermute_b32 v31, v137, v151
	s_waitcnt lgkmcnt(0)
	v_lshl_add_u32 v16, v16, 10, v138
	v_lshl_add_u32 v17, v17, 10, v138
	v_lshl_add_u32 v18, v18, 10, v138
	v_lshl_add_u32 v19, v19, 10, v138
	v_lshl_add_u32 v20, v20, 10, v138
	v_lshl_add_u32 v21, v21, 10, v138
	v_lshl_add_u32 v22, v22, 10, v138
	v_lshl_add_u32 v23, v23, 10, v138
	v_lshl_add_u32 v24, v24, 10, v138
	v_lshl_add_u32 v25, v25, 10, v138
	v_lshl_add_u32 v26, v26, 10, v138
	v_lshl_add_u32 v27, v27, 10, v138
	v_lshl_add_u32 v28, v28, 10, v138
	v_lshl_add_u32 v29, v29, 10, v138
	v_lshl_add_u32 v30, v30, 10, v138
	v_lshl_add_u32 v31, v31, 10, v138
	v_lshlrev_b32_e32 v0, 16, v152
	v_and_b32_e32 v1, 0xffff0000, v152
	v_lshlrev_b32_e32 v2, 16, v153
	v_and_b32_e32 v3, 0xffff0000, v153
	v_lshlrev_b32_e32 v4, 16, v154
	v_and_b32_e32 v5, 0xffff0000, v154
	v_lshlrev_b32_e32 v6, 16, v155
	v_and_b32_e32 v7, 0xffff0000, v155
	v_lshlrev_b32_e32 v8, 16, v156
	v_and_b32_e32 v9, 0xffff0000, v156
	v_lshlrev_b32_e32 v10, 16, v157
	v_and_b32_e32 v11, 0xffff0000, v157
	v_lshlrev_b32_e32 v12, 16, v158
	v_and_b32_e32 v13, 0xffff0000, v158
	v_lshlrev_b32_e32 v14, 16, v159
	v_and_b32_e32 v15, 0xffff0000, v159

.Lgy_C_3:
	v_lshrrev_b32_e32 v142, 6, v162
	v_readlane_b32 s2, v242, 0
	v_readlane_b32 s59, v241, 24
	v_readfirstlane_b32 s29, v142
	s_and_b32 s28, s2, 7
	s_lshr_b32 s2, s2, 3
	s_lshl_b32 s2, s2, 2
	s_add_u32 s54, s2, s29
	s_lshr_b32 s59, s59, 3
	s_load_dwordx2 s[88:89], s[0:1], 0x1a8
	s_load_dwordx2 s[90:91], s[0:1], 0x1b0
	s_load_dwordx2 s[92:93], s[0:1], 0x120
	s_load_dwordx2 s[94:95], s[0:1], 0xc8
	v_readlane_b32 s40, v240, 10
	v_readlane_b32 s41, v240, 11
	v_and_b32_e32 v142, 7, v168
	v_lshlrev_b32_e32 v160, 2, v168
	s_lshl_b32 s32, s28, 7
	v_lshl_add_u32 v138, v142, 4, s32
	v_and_b32_e32 v143, 0xf8, v168
	v_add_u32_e32 v130, 0, v143
	v_add_u32_e32 v131, 1, v143
	v_add_u32_e32 v132, 2, v143
	v_add_u32_e32 v133, 3, v143
	v_add_u32_e32 v134, 4, v143
	v_add_u32_e32 v135, 5, v143
	v_add_u32_e32 v136, 6, v143
	v_add_u32_e32 v137, 7, v143
	v_lshlrev_b32_e32 v130, 2, v130
	v_lshlrev_b32_e32 v131, 2, v131
	v_lshlrev_b32_e32 v132, 2, v132
	v_lshlrev_b32_e32 v133, 2, v133
	v_lshlrev_b32_e32 v134, 2, v134
	v_lshlrev_b32_e32 v135, 2, v135
	v_lshlrev_b32_e32 v136, 2, v136
	v_lshlrev_b32_e32 v137, 2, v137
	v_lshrrev_b32_e32 v144, 3, v168
	v_lshlrev_b32_e32 v144, 3, v144
	s_lshl_b32 s32, s28, 9
	v_lshl_add_u32 v188, v142, 6, s32
	v_add_u32_e32 v188, v188, v144
	s_mov_b32 s16, 0x3fd744fd
	s_waitcnt lgkmcnt(0)
	s_nop 4
	s_cmp_lt_u32 s54, 0x4200
	s_cbranch_scc0 .Lgy_Cdone_10
	s_min_u32 s98, s54, 0x41ff
	s_lshl_b32 s98, s98, 9
	s_add_u32 s52, s88, s98
	s_addc_u32 s53, s89, 0
	global_load_dword v144, v160, s[52:53]
	global_load_dword v145, v160, s[52:53] offset:256
	s_add_u32 s99, s54, s59
	s_min_u32 s98, s99, 0x41ff
	s_lshl_b32 s98, s98, 9
	s_add_u32 s52, s88, s98
	s_addc_u32 s53, s89, 0
	global_load_dword v150, v160, s[52:53]
	global_load_dword v151, v160, s[52:53] offset:256
	s_min_u32 s98, s54, 0x41ff
	s_lshl_b32 s98, s98, 9
	s_add_u32 s52, s90, s98
	s_addc_u32 s53, s91, 0
	global_load_dword v194, v160, s[52:53]
	global_load_dword v195, v160, s[52:53] offset:256
	s_waitcnt vmcnt(0)
	ds_bpermute_b32 v16, v130, v144
	ds_bpermute_b32 v17, v131, v144
	ds_bpermute_b32 v18, v132, v144
	ds_bpermute_b32 v19, v133, v144
	ds_bpermute_b32 v20, v134, v144
	ds_bpermute_b32 v21, v135, v144
	ds_bpermute_b32 v22, v136, v144
	ds_bpermute_b32 v23, v137, v144
	ds_bpermute_b32 v24, v130, v145
	ds_bpermute_b32 v25, v131, v145
	ds_bpermute_b32 v26, v132, v145
	ds_bpermute_b32 v27, v133, v145
	ds_bpermute_b32 v28, v134, v145
	ds_bpermute_b32 v29, v135, v145
	ds_bpermute_b32 v30, v136, v145
	ds_bpermute_b32 v31, v137, v145
	s_waitcnt lgkmcnt(0)
	v_lshl_add_u32 v16, v16, 10, v138
	v_lshl_add_u32 v17, v17, 10, v138
	v_lshl_add_u32 v18, v18, 10, v138
	v_lshl_add_u32 v19, v19, 10, v138
	v_lshl_add_u32 v20, v20, 10, v138
	v_lshl_add_u32 v21, v21, 10, v138
	v_lshl_add_u32 v22, v22, 10, v138
	v_lshl_add_u32 v23, v23, 10, v138
	v_lshl_add_u32 v24, v24, 10, v138
	v_lshl_add_u32 v25, v25, 10, v138
	v_lshl_add_u32 v26, v26, 10, v138
	v_lshl_add_u32 v27, v27, 10, v138
	v_lshl_add_u32 v28, v28, 10, v138
	v_lshl_add_u32 v29, v29, 10, v138
	v_lshl_add_u32 v30, v30, 10, v138
	v_lshl_add_u32 v31, v31, 10, v138
	global_load_dwordx4 v[48:51], v16, s[40:41]
	global_load_dwordx4 v[52:55], v17, s[40:41]
	global_load_dwordx4 v[56:59], v18, s[40:41]
	global_load_dwordx4 v[60:63], v19, s[40:41]
	global_load_dwordx4 v[64:67], v20, s[40:41]
	global_load_dwordx4 v[68:71], v21, s[40:41]
	global_load_dwordx4 v[72:75], v22, s[40:41]
	global_load_dwordx4 v[76:79], v23, s[40:41]
	global_load_dwordx4 v[80:83], v24, s[40:41]
	global_load_dwordx4 v[84:87], v25, s[40:41]
	global_load_dwordx4 v[88:91], v26, s[40:41]
	global_load_dwordx4 v[92:95], v27, s[40:41]
	global_load_dwordx4 v[96:99], v28, s[40:41]
	global_load_dwordx4 v[100:103], v29, s[40:41]
	global_load_dwordx4 v[104:107], v30, s[40:41]
	global_load_dwordx4 v[108:111], v31, s[40:41]
	ds_bpermute_b32 v16, v130, v150
	ds_bpermute_b32 v17, v131, v150
	ds_bpermute_b32 v18, v132, v150
	ds_bpermute_b32 v19, v133, v150
	ds_bpermute_b32 v20, v134, v150
	ds_bpermute_b32 v21, v135, v150
	ds_bpermute_b32 v22, v136, v150
	ds_bpermute_b32 v23, v137, v150
	ds_bpermute_b32 v24, v130, v151
	ds_bpermute_b32 v25, v131, v151
	ds_bpermute_b32 v26, v132, v151
	ds_bpermute_b32 v27, v133, v151
	ds_bpermute_b32 v28, v134, v151
	ds_bpermute_b32 v29, v135, v151
	ds_bpermute_b32 v30, v136, v151
	ds_bpermute_b32 v31, v137, v151
	s_waitcnt lgkmcnt(0)
	v_lshl_add_u32 v16, v16, 10, v138
	v_lshl_add_u32 v17, v17, 10, v138
	v_lshl_add_u32 v18, v18, 10, v138
	v_lshl_add_u32 v19, v19, 10, v138
	v_lshl_add_u32 v20, v20, 10, v138
	v_lshl_add_u32 v21, v21, 10, v138
	v_lshl_add_u32 v22, v22, 10, v138
	v_lshl_add_u32 v23, v23, 10, v138
	v_lshl_add_u32 v24, v24, 10, v138
	v_lshl_add_u32 v25, v25, 10, v138
	v_lshl_add_u32 v26, v26, 10, v138
	v_lshl_add_u32 v27, v27, 10, v138
	v_lshl_add_u32 v28, v28, 10, v138
	v_lshl_add_u32 v29, v29, 10, v138
	v_lshl_add_u32 v30, v30, 10, v138
	v_lshl_add_u32 v31, v31, 10, v138
	ds_bpermute_b32 v32, v130, v194
	ds_bpermute_b32 v33, v131, v194
	ds_bpermute_b32 v34, v132, v194
	ds_bpermute_b32 v35, v133, v194
	ds_bpermute_b32 v36, v134, v194
	ds_bpermute_b32 v37, v135, v194
	ds_bpermute_b32 v38, v136, v194
	ds_bpermute_b32 v39, v137, v194
	ds_bpermute_b32 v40, v130, v195
	ds_bpermute_b32 v41, v131, v195
	ds_bpermute_b32 v42, v132, v195
	ds_bpermute_b32 v43, v133, v195
	ds_bpermute_b32 v44, v134, v195
	ds_bpermute_b32 v45, v135, v195
	ds_bpermute_b32 v46, v136, v195
	ds_bpermute_b32 v47, v137, v195
